# lever 4: static s_setprio 1 for waves 4-7 (second head of the pair) during the attention phase
# baseline (speedup 1.0000x reference)
; DI int v_st(int k, int c) { const int kk = (k & ~0xC) | ((k & 4) << 1) | ((k & 8) >> 1); return ((kk >> 3) * 4 + (c >> 5)) * 512 + ((kk & 7) * 32 + (c & 31)) * 2; }
; DI int v_rd_base(int lane) { return ((lane & 3) << 3) | (((lane >> 2) & 3) << 6) | (((lane >> 4) & 1) << 5) | (((lane >> 5) & 1) << 8); }
; DI void attn_item(const bf16_t* __restrict__ Qw_, const bf16_t* __restrict__ Kh, const bf16_t* __restrict__ Vh, const bf16_t* Gw, bf16_t* Ow,
;                   int NT, int kt0, int qw, float sinkv, char* lds) {
;     const int tid = threadIdx.x, wid = __builtin_amdgcn_readfirstlane(tid >> 6), lane = tid & 63, r32 = lane & 31, hi = lane >> 5;
;     char* V_lds = lds; char* K_lds = lds + 2 * SHM_V;
;     float* wsp = (float*)(lds + 2 * SHM_V + 2 * SHM_K) + wid * 64; float* li_l = wsp; float* al_l = wsp + 32;
;     float m_reg = sinkv * (1.f / SCALE), l_reg = 1.f; f32x16 o[4]; bf16x8 qr[8];
; #pragma unroll
;     for (int d = 0; d < 4; ++d)
; #pragma unroll
;         for (int r = 0; r < 16; ++r) o[d][r] = 0.f;
;     const bf16_t* Qw = Qw_ + (size_t)r32 * LDK + hi * 8;
; #pragma unroll
;     for (int d0 = 0; d0 < 8; ++d0) qr[d0] = *(const bf16x8*)(Qw + d0 * 16);
;     const int sr = tid >> 4, sc = (tid & 15) * 8, vst0 = v_st(sr, sc), vst1 = v_st(32 + sr, sc);
;     const int vb0 = (int)(uintptr_t)V_lds + v_rd_base(lane);
; DI void phase_att(const Params& p, unsigned char* shm) {
;     const int wid = __builtin_amdgcn_readfirstlane(threadIdx.x >> 6);
;     const bf16_t* Z = (const bf16_t*)(p.ws + WS_ZQKV); const bf16_t* GA = (const bf16_t*)(p.ws + WS_ZGA); bf16_t* YB = (bf16_t*)(p.ws + WS_YB);
;     for (int it = blockIdx.x; it < 1024; it += gridDim.x) {
;         const int hp = it & 1, g = (it >> 1) & 3, n = it >> 3;
;         const int head = g * 4 + hp * 2 + (wid >> 2), qw = 32 * (wid & 3);
;         const int kfirst = n == 0 ? 0 : (n - 1) * 128, NT = (n == 0 || n == 127) ? 4 : 6, kt0 = kfirst - n * 128;
.LBB0_234:
	s_bitcmp0_b32 s4, 1
	s_cbranch_scc1 .LBB0_266
	s_cmpk_gt_i32 s2, 0x3ff
	v_readfirstlane_b32 s6, v202
	s_cbranch_scc1 .LBB0_265
	v_lshrrev_b32_e32 v180, 4, v202
	s_load_dwordx2 s[4:5], s[0:1], 0x80
	s_load_dwordx2 s[8:9], s[0:1], 0x50
	s_waitcnt vmcnt(0)
	v_add_u32_e32 v10, 32, v180
	v_and_b32_e32 v5, 48, v180
	v_lshrrev_b32_e32 v6, 3, v202
	v_and_b32_e32 v11, 0x70, v10
	v_lshlrev_b32_e32 v12, 1, v10
	v_lshlrev_b32_e32 v3, 3, v202
	v_and_or_b32 v5, v6, 8, v5
	v_and_or_b32 v11, v12, 8, v11
	v_and_b32_e32 v4, 0x78, v3
	v_lshrrev_b32_e32 v5, 1, v5
	v_bfe_u32 v6, v3, 5, 2
	v_bfe_u32 v7, v202, 4, 2
	v_lshrrev_b32_e32 v11, 1, v11
	s_waitcnt lgkmcnt(0)
	s_add_u32 s11, s4, 0x8000000
	v_or_b32_e32 v5, v5, v6
	v_and_or_b32 v7, v203, 4, v7
	v_lshlrev_b32_e32 v8, 1, v4
	v_or_b32_e32 v6, v11, v6
	s_addc_u32 s22, s5, 0
	v_lshlrev_b32_e32 v5, 9, v5
	v_lshlrev_b32_e32 v7, 6, v7
	v_and_b32_e32 v9, 48, v8
	v_lshlrev_b32_e32 v6, 9, v6
	s_add_u32 s23, s4, 0xe000000
	v_or3_b32 v5, v5, v7, v9
	v_or3_b32 v7, v6, v7, v9
	v_lshlrev_b32_e32 v9, 4, v202
	v_lshlrev_b32_e32 v11, 1, v202
	s_addc_u32 s30, s5, 0
	s_lshr_b32 s31, s6, 8
	s_lshr_b32 s6, s6, 1
	v_bfe_u32 v0, v202, 5, 1
	v_and_b32_e32 v6, 0xc0, v9
	v_and_b32_e32 v11, 32, v11
	v_and_b32_e32 v3, 0x118, v3
	v_and_b32_e32 v188, 31, v202
	s_and_b32 s34, s6, 0x60
	v_or3_b32 v3, v11, v6, v3
	v_lshlrev_b32_e32 v11, 8, v180
	v_and_b32_e32 v12, 0x70, v202
	v_lshlrev_b32_e32 v10, 8, v10
	v_lshlrev_b32_e32 v191, 4, v0
	s_cmp_lg_u32 0, -1
	v_bitop3_b32 v11, v8, v11, v12 bitop3:0xde
	v_bitop3_b32 v13, v8, v10, v12 bitop3:0xde
	v_lshlrev_b32_e32 v8, 8, v188
	v_and_b32_e32 v9, 0x70, v9
	v_or_b32_e32 v10, 32, v191
	s_cselect_b32 s10, 0, 0
	v_bitop3_b32 v18, v10, v8, v9 bitop3:0xde
	v_or_b32_e32 v10, 64, v191
	v_add_u32_e32 v190, s10, v3
	v_bitop3_b32 v19, v10, v8, v9 bitop3:0xde
	v_or_b32_e32 v10, 0x60, v191
	v_lshlrev_b32_e32 v193, 2, v0
	s_addk_i32 s10, 0x4000
	v_lshlrev_b32_e32 v2, 3, v0
	v_bitop3_b32 v20, v10, v8, v9 bitop3:0xde
	v_or_b32_e32 v10, 0x80, v191
	v_add_u32_e32 v194, s10, v3
	v_mul_u32_u24_e32 v196, 0x440, v0
	v_or_b32_e32 v0, 1, v193
	s_movk_i32 s39, 0x110
	v_mov_b32_e32 v3, 0x990
	v_bitop3_b32 v21, v10, v8, v9 bitop3:0xde
	v_or_b32_e32 v10, 0xa0, v191
	v_mul_u32_u24_e32 v197, 0x110, v0
	v_mad_u32_u24 v198, v0, s39, v3
	v_sub_u32_e32 v0, v193, v188
	v_mul_u32_u24_e32 v6, 0xc00, v180
	v_bitop3_b32 v22, v10, v8, v9 bitop3:0xde
	v_or_b32_e32 v10, 0xc0, v191
	v_subrev_u32_e32 v199, s34, v0
	v_and_b32_e32 v0, 15, v202
	v_mov_b32_e32 v1, 0
	v_or_b32_e32 v4, v6, v4
	v_bitop3_b32 v23, v10, v8, v9 bitop3:0xde
	v_or_b32_e32 v10, 0xe0, v191
	v_lshlrev_b32_e32 v0, 4, v0
	v_and_b32_e32 v189, 63, v202
	v_add_u32_e32 v6, 0x18000, v4
	v_bitop3_b32 v15, v191, v8, v9 bitop3:0xde
	v_bitop3_b32 v9, v10, v8, v9 bitop3:0xde
	v_or_b32_e32 v192, s34, v188
	v_add_u32_e32 v8, 0x30000, v4
	v_add_u32_e32 v10, 0x48000, v4
	v_add_u32_e32 v12, 0x78000, v4
	v_add_u32_e32 v14, 0x60000, v4
	v_lshl_add_u64 v[16:17], s[4:5], 0, v[0:1]
	s_mov_b64 s[4:5], 0x81b1400
	s_movk_i32 s35, 0x1800
	v_mul_u32_u24_e32 v178, 0x1800, v188
	v_mov_b32_e32 v179, v1
	s_mov_b32 s36, 0x18000
	s_or_b32 s37, s6, 0xffffff9f
	v_cmp_gt_u32_e64 s[6:7], 32, v189
	s_movk_i32 s38, 0x4000
	v_sub_u32_e32 v195, v193, v192
	s_sub_i32 s40, 0, s34
	v_lshl_add_u64 v[182:183], v[16:17], 0, s[4:5]
	v_mov_b32_e32 v181, v1
	v_lshlrev_b32_e32 v184, 1, v2
	v_lshlrev_b32_e32 v200, 1, v4
	v_lshlrev_b32_e32 v201, 1, v6
	s_movk_i32 s41, 0x101
	s_mov_b32 s42, 0x10000
	s_mov_b32 s43, 0x413504f3
	s_mov_b32 s44, 0x42b504f3
	s_mov_b32 s10, 0x3e0293ee
	v_lshlrev_b32_e32 v204, 1, v8
	v_lshlrev_b32_e32 v205, 1, v10
	v_lshlrev_b32_e32 v206, 1, v12
	v_lshlrev_b32_e32 v207, 1, v14
	s_mov_b32 s45, 0xfff70000
	s_mov_b32 s46, 0xfffa0000
	s_mov_b64 s[12:13], 0xc0000
	s_mov_b32 s47, 0x8000
	s_mov_b32 s48, 0xc000
	s_mov_b32 s49, 0x14000
	s_mov_b32 s50, 0x1c000
	v_mov_b32_e32 v185, v1
	v_add_u32_e32 v208, 0, v5
	v_add_u32_e32 v209, 0, v7
	v_add_u32_e32 v210, 0, v11
	v_add_u32_e32 v211, 0, v13
	v_add_u32_e32 v212, 0, v15
	v_add_u32_e32 v213, 0, v18
	v_add_u32_e32 v214, 0, v19
	v_add_u32_e32 v215, 0, v20
	v_add_u32_e32 v216, 0, v21
	v_add_u32_e32 v217, 0, v22
	v_add_u32_e32 v218, 0, v23
	v_add_u32_e32 v219, 0, v9
	v_mov_b32_e32 v220, 0xf149f2ca
	v_readfirstlane_b32 s90, v202
	s_cmp_ge_u32 s90, 0x100
	s_cbranch_scc0 .Lprio_att
	s_setprio 1
.Lprio_att:
	s_mov_b32 s51, s2
	s_branch .LBB0_238

; DI void phase_att(const Params& p, unsigned char* shm) {
;     ...
;     __syncthreads();
.LBB0_265:
	s_setprio 0
	s_waitcnt vmcnt(0)
	s_barrier
